# LayerNorm row loop: all twelve row/gamma/beta loads issued up front (on top of merge K-loop load hoisting)
# baseline (speedup 1.0000x reference)
;   __device__ __forceinline__ const float* x() const { return (const float*)(const __attribute__((address_space(1))) float*)kp[0]; }
;   __device__ __forceinline__ const float* ln_g() const { return (const float*)(const __attribute__((address_space(1))) float*)kp[16]; }
;   __device__ __forceinline__ const float* ln_b() const { return (const float*)(const __attribute__((address_space(1))) float*)kp[17]; }
;   __device__ __forceinline__ float* out() const { return (float*)(__attribute__((address_space(1))) float*)kp[18]; }
; __device__ __forceinline__ void ln_rows(const KP& p, int lprev, bool final_) {
;     ...
;   for (int row = gw; row < NTOK; row += nw) {
;     const float4* rp = (const float4*)((lprev < 0 ? p.x() : (const float*)p.u()) + (size_t)row * DM);
;     float4 v[4];
;     float s = 0.f;
; #pragma unroll
;     for (int i = 0; i < 4; ++i) {
;       v[i] = rp[lane + 64 * i];
;       s += v[i].x + v[i].y + v[i].z + v[i].w;
;     }
;     if (lprev >= 0) {
;       float mu = wave_sum(s) * (1.f / DM);
;       float q = 0.f;
; #pragma unroll
;       for (int i = 0; i < 4; ++i) {
;         float a = v[i].x - mu, b = v[i].y - mu, c = v[i].z - mu, d = v[i].w - mu;
;         q += a * a + b * b + c * c + d * d;
;       }
;       float rstd = rsqrtf(wave_sum(q) * (1.f / DM) + 1e-5f);
;       const float4* g4 = (const float4*)(p.ln_g() + lprev * DM);
;       const float4* b4 = (const float4*)(p.ln_b() + lprev * DM);
; #pragma unroll
;       for (int i = 0; i < 4; ++i) {
;         float4 g = g4[lane + 64 * i], bb = b4[lane + 64 * i];
;         v[i].x = (v[i].x - mu) * rstd * g.x + bb.x;
;         v[i].y = (v[i].y - mu) * rstd * g.y + bb.y;
;         v[i].z = (v[i].z - mu) * rstd * g.z + bb.z;
;         v[i].w = (v[i].w - mu) * rstd * g.w + bb.w;
;       }
;     }
;     if (final_) {
;       float4* op = (float4*)(p.out() + (size_t)row * DM);
; #pragma unroll
;       for (int i = 0; i < 4; ++i) op[lane + 64 * i] = v[i];
;     } else {
;       float4* op = (float4*)(p.xr() + (size_t)row * DM);
;       h4* hp = (h4*)(p.xh() + (size_t)row * DM);
; #pragma unroll
;       for (int i = 0; i < 4; ++i) {
;         op[lane + 64 * i] = v[i];
;         h4 hv;
;         hv[0] = (half_t)v[i].x; hv[1] = (half_t)v[i].y; hv[2] = (half_t)v[i].z; hv[3] = (half_t)v[i].w;
;         hp[lane + 64 * i] = hv;
;       }
;     }
;   }
.LBB0_1870:
	v_lshl_add_u32 v76, v2, 6, v77
	v_lshl_add_u64 v[66:67], s[16:17], 0, v[10:11]
	v_add_co_u32_e32 v54, vcc, 0x6000000, v66
	v_lshl_add_u64 v[68:69], s[16:17], 0, v[8:9]
	s_nop 0
	v_addc_co_u32_e32 v55, vcc, 0, v67, vcc
	global_load_dwordx4 v[18:21], v[54:55], off
	global_load_dwordx4 v[22:25], v[4:5], off
	global_load_dwordx4 v[26:29], v[6:7], off
	global_load_dwordx4 v[30:33], v[54:55], off offset:1024
	global_load_dwordx4 v[34:37], v[4:5], off offset:1024
	global_load_dwordx4 v[38:41], v[6:7], off offset:1024
	global_load_dwordx4 v[42:45], v[54:55], off offset:2048
	global_load_dwordx4 v[46:49], v[4:5], off offset:2048
	global_load_dwordx4 v[50:53], v[6:7], off offset:2048
	global_load_dwordx4 v[54:57], v[54:55], off offset:3072
	global_load_dwordx4 v[58:61], v[4:5], off offset:3072
	global_load_dwordx4 v[62:65], v[6:7], off offset:3072
	v_add_u32_e32 v2, s48, v2
	v_lshl_add_u64 v[8:9], v[8:9], 0, s[70:71]
	v_lshl_add_u64 v[10:11], v[10:11], 0, s[78:79]
	s_waitcnt vmcnt(11)
	v_mov_b32_e32 v70, v18
	s_waitcnt vmcnt(8)
	v_mov_b32_e32 v71, v30
	v_mov_b32_e32 v72, v19
	v_mov_b32_e32 v73, v31
	v_pk_add_f32 v[70:71], v[70:71], v[72:73]
	v_mov_b32_e32 v72, v20
	v_mov_b32_e32 v73, v32
	v_pk_add_f32 v[70:71], v[70:71], v[72:73]
	v_mov_b32_e32 v72, v21
	v_mov_b32_e32 v73, v33
	v_pk_add_f32 v[70:71], v[70:71], v[72:73]
	s_nop 0
	v_add_f32_e32 v0, 0, v70
	v_add_f32_e32 v0, v0, v71
	s_waitcnt vmcnt(5)
	v_mov_b32_e32 v70, v42
	v_mov_b32_e32 v72, v43
	s_waitcnt vmcnt(2)
	v_mov_b32_e32 v71, v54
	v_mov_b32_e32 v73, v55
	v_pk_add_f32 v[70:71], v[70:71], v[72:73]
	v_mov_b32_e32 v72, v44
	v_mov_b32_e32 v73, v56
	v_pk_add_f32 v[70:71], v[70:71], v[72:73]
	v_mov_b32_e32 v72, v45
	v_mov_b32_e32 v73, v57
	v_pk_add_f32 v[70:71], v[70:71], v[72:73]
	s_nop 0
	v_add_f32_e32 v0, v0, v70
	v_add_f32_e32 v0, v0, v71
	ds_bpermute_b32 v3, v12, v0
	s_waitcnt lgkmcnt(0)
	v_add_f32_e32 v0, v0, v3
	ds_bpermute_b32 v3, v13, v0
	s_waitcnt lgkmcnt(0)
	v_add_f32_e32 v0, v0, v3
	ds_bpermute_b32 v3, v14, v0
	s_waitcnt lgkmcnt(0)
	v_add_f32_e32 v0, v0, v3
	ds_bpermute_b32 v3, v15, v0
	s_waitcnt lgkmcnt(0)
	v_add_f32_e32 v0, v0, v3
	ds_bpermute_b32 v3, v16, v0
	s_waitcnt lgkmcnt(0)
	v_add_f32_e32 v0, v0, v3
	ds_bpermute_b32 v3, v17, v0
	s_waitcnt lgkmcnt(0)
	v_add_f32_e32 v0, v0, v3
	v_mul_f32_e32 v0, 0x3a800000, v0
	v_pk_add_f32 v[18:19], v[18:19], v[0:1] op_sel_hi:[1,0] neg_lo:[0,1] neg_hi:[0,1]
	v_pk_add_f32 v[30:31], v[30:31], v[0:1] op_sel_hi:[1,0] neg_lo:[0,1] neg_hi:[0,1]
	v_mov_b32_e32 v72, v19
	v_mov_b32_e32 v73, v31
	v_pk_add_f32 v[20:21], v[20:21], v[0:1] op_sel_hi:[1,0] neg_lo:[0,1] neg_hi:[0,1]
	v_pk_add_f32 v[32:33], v[32:33], v[0:1] op_sel_hi:[1,0] neg_lo:[0,1] neg_hi:[0,1]
	v_mov_b32_e32 v70, v18
	v_mov_b32_e32 v71, v30
	v_pk_mul_f32 v[72:73], v[72:73], v[72:73]
	v_pk_add_f32 v[42:43], v[42:43], v[0:1] op_sel_hi:[1,0] neg_lo:[0,1] neg_hi:[0,1]
	v_pk_fma_f32 v[70:71], v[70:71], v[70:71], v[72:73]
	v_mov_b32_e32 v72, v20
	v_mov_b32_e32 v73, v32
	v_pk_add_f32 v[54:55], v[54:55], v[0:1] op_sel_hi:[1,0] neg_lo:[0,1] neg_hi:[0,1]
	v_pk_fma_f32 v[70:71], v[72:73], v[72:73], v[70:71]
	v_mov_b32_e32 v72, v21
	v_mov_b32_e32 v73, v33
	v_mov_b32_e32 v74, v55
	v_mov_b32_e32 v75, v43
	v_pk_fma_f32 v[70:71], v[72:73], v[72:73], v[70:71]
	v_pk_add_f32 v[44:45], v[44:45], v[0:1] op_sel_hi:[1,0] neg_lo:[0,1] neg_hi:[0,1]
	v_pk_add_f32 v[56:57], v[56:57], v[0:1] op_sel_hi:[1,0] neg_lo:[0,1] neg_hi:[0,1]
	v_mov_b32_e32 v72, v54
	v_mov_b32_e32 v73, v42
	v_pk_mul_f32 v[74:75], v[74:75], v[74:75]
	v_add_f32_e32 v0, v70, v71
	v_pk_fma_f32 v[72:73], v[72:73], v[72:73], v[74:75]
	v_mov_b32_e32 v74, v56
	v_mov_b32_e32 v75, v44
	v_pk_fma_f32 v[72:73], v[74:75], v[74:75], v[72:73]
	v_mov_b32_e32 v74, v57
	v_mov_b32_e32 v75, v45
	v_pk_fma_f32 v[72:73], v[74:75], v[74:75], v[72:73]
	s_nop 0
	v_add_f32_e32 v0, v73, v0
	v_add_f32_e32 v0, v72, v0
	ds_bpermute_b32 v3, v12, v0
	s_waitcnt lgkmcnt(0)
	v_add_f32_e32 v0, v0, v3
	ds_bpermute_b32 v3, v13, v0
	s_waitcnt lgkmcnt(0)
	v_add_f32_e32 v0, v0, v3
	ds_bpermute_b32 v3, v14, v0
	s_waitcnt lgkmcnt(0)
	v_add_f32_e32 v0, v0, v3
	ds_bpermute_b32 v3, v15, v0
	s_waitcnt lgkmcnt(0)
	v_add_f32_e32 v0, v0, v3
	ds_bpermute_b32 v3, v16, v0
	s_waitcnt lgkmcnt(0)
	v_add_f32_e32 v0, v0, v3
	ds_bpermute_b32 v3, v17, v0
	s_waitcnt lgkmcnt(0)
	v_add_f32_e32 v0, v0, v3
	v_fmamk_f32 v0, v0, 0x3a800000, v231
	v_cmp_gt_f32_e32 vcc, s66, v0
	v_mul_f32_e32 v3, 0x4b800000, v0
	s_nop 0
	v_cndmask_b32_e32 v0, v0, v3, vcc
	v_rsq_f32_e32 v0, v0
	s_nop 0
	v_mul_f32_e32 v3, 0x45800000, v0
	v_cndmask_b32_e32 v0, v0, v3, vcc
	v_pk_mul_f32 v[18:19], v[18:19], v[0:1] op_sel_hi:[1,0]
	v_pk_mul_f32 v[20:21], v[20:21], v[0:1] op_sel_hi:[1,0]
	v_pk_fma_f32 v[18:19], v[22:23], v[18:19], v[26:27]
	v_pk_fma_f32 v[20:21], v[24:25], v[20:21], v[28:29]
	v_pk_mul_f32 v[22:23], v[30:31], v[0:1] op_sel_hi:[1,0]
	v_pk_mul_f32 v[24:25], v[32:33], v[0:1] op_sel_hi:[1,0]
	global_store_dwordx4 v[66:67], v[18:21], off
	v_pk_fma_f32 v[22:23], v[34:35], v[22:23], v[38:39]
	v_pk_fma_f32 v[24:25], v[36:37], v[24:25], v[40:41]
	v_cvt_pk_f16_f32 v21, v20, v21
	v_cvt_pk_f16_f32 v20, v18, v19
	v_add_co_u32_e32 v18, vcc, s4, v68
	v_pk_mul_f32 v[26:27], v[42:43], v[0:1] op_sel_hi:[1,0]
	v_pk_mul_f32 v[28:29], v[44:45], v[0:1] op_sel_hi:[1,0]
	v_addc_co_u32_e32 v19, vcc, 0, v69, vcc
	v_pk_fma_f32 v[26:27], v[46:47], v[26:27], v[50:51]
	v_pk_fma_f32 v[28:29], v[28:29], v[48:49], v[52:53]
	v_pk_mul_f32 v[30:31], v[54:55], v[0:1] op_sel_hi:[1,0]
	v_pk_mul_f32 v[32:33], v[56:57], v[0:1] op_sel_hi:[1,0]
	global_store_dwordx2 v76, v[20:21], s[16:17]
	global_store_dwordx4 v[66:67], v[22:25], off offset:1024
	v_cvt_pk_f16_f32 v21, v24, v25
	v_cvt_pk_f16_f32 v20, v22, v23
	s_waitcnt vmcnt(3)
	v_pk_fma_f32 v[30:31], v[30:31], v[58:59], v[62:63]
	v_pk_fma_f32 v[32:33], v[32:33], v[60:61], v[64:65]
	v_add_u32_e32 v78, 0x800000, v76
	global_store_dwordx2 v78, v[20:21], s[16:17]
	global_store_dwordx4 v[66:67], v[26:29], off offset:2048
	v_cvt_pk_f16_f32 v21, v28, v29
	v_cvt_pk_f16_f32 v20, v26, v27
	v_cmp_lt_i32_e32 vcc, s67, v2
	v_add_u32_e32 v79, 0x1000000, v76
	global_store_dwordx2 v79, v[20:21], s[16:17]
	global_store_dwordx4 v[66:67], v[30:33], off offset:3072
	v_cvt_pk_f16_f32 v21, v32, v33
	v_cvt_pk_f16_f32 v20, v30, v31
	s_or_b64 s[18:19], vcc, s[18:19]
	v_add_u32_e32 v80, 0x1800000, v76
	global_store_dwordx2 v80, v[20:21], s[16:17]
	s_andn2_b64 exec, exec, s[18:19]
	s_cbranch_execnz .LBB0_1870
